# PH1 GEMM loop also converted to SGPR-base LDS-DMA addressing (on top of PH8)
# speedup vs baseline: 1.0095x; 1.0019x over previous
; #define PG8_STAGE(bufoff, gbase, RR, ld) do { _Pragma("unroll") for (int _i = 0; _i < 2; ++_i) \
;         __builtin_amdgcn_global_load_lds((const unsigned*)((const char*)(gbase) + (RR)[_i] * (ld) + C2[_i]), (LAS unsigned*)(lds + (bufoff) + ldsw + _i * 8192), 16, 0, 0); } while (0)
; #define PG8_WAIT_V(n) asm volatile("s_waitcnt vmcnt(" #n ")" ::: "memory")
; #define PG8_BAR __builtin_amdgcn_s_barrier()
; template <class Sched, class Epi>
; __device__ __forceinline__ void gemm_run(LAS unsigned char* lds, const Sched& S, const Epi& E) {
;     const int tid = threadIdx.x, wid = __builtin_amdgcn_readfirstlane(tid >> 6), lane = tid & 63, wr = wid >> 2, wc = wid & 3, fr = lane & 15, fq = lane >> 4;
;     unsigned RA[2], RB[2], C2[2];
; #pragma unroll
;     for (int i = 0; i < 2; ++i) { int R, C; stage_rc(tid * 16 + i * 8192, R, C); RA[i] = (unsigned)R; RB[i] = (unsigned)((R & ~31) + perm32(R & 31)); C2[i] = (unsigned)(C * 2); }
;     const unsigned ldsw = (unsigned)wid * 1024u;
;     const int aoff = lds_byte(wr * 64 + fr, fq * 8), boff = lds_byte(wc * 32 + fr, fq * 8);
;     ...
;     Unit cur, nxt; int ui = 0;
;     if (!S.next(0, cur)) return;
;     f32x4 acc[2][2][4][2];
; #pragma unroll
;     for (int a = 0; a < 2; ++a)
; #pragma unroll
;         for (int b = 0; b < 2; ++b)
; #pragma unroll
;             for (int m = 0; m < 4; ++m)
; #pragma unroll
;                 for (int n = 0; n < 2; ++n) acc[a][b][m][n] = (f32x4){0.f, 0.f, 0.f, 0.f};
;     bf16x8 At[4][2], B0[2][2], B1[2][2];
;     const char* cA = cur.A; const char* cB = cur.B; unsigned lda = cur.lda, ldb = cur.ldb;
;     constexpr unsigned kstep = BK * 2;
;     PG8_STAGE(PG8_SB(0, 0), cB, RB, ldb); PG8_STAGE(PG8_SB(0, 1), cB + (size_t)HALF * ldb, RB, ldb); PG8_STAGE(PG8_SA(0, 0), cA, RA, lda); PG8_STAGE(PG8_SA(0, 1), cA + (size_t)HALF * lda, RA, lda);
;     if (wr == 1) PG8_BAR;
;     PG8_WAIT_V(2); PG8_BAR;
;     PG8_STAGE(PG8_SB(1, 0), cB + kstep, RB, ldb); PG8_STAGE(PG8_SA(1, 0), cA + kstep, RA, lda); PG8_STAGE(PG8_SB(1, 1), cB + (size_t)HALF * ldb + kstep, RB, ldb);
;     PG8_WAIT_V(6); PG8_BAR;
.LBB0_240:
	s_lshl_b32 s63, s0, 6
	s_lshl_b32 s16, s0, 13
	s_lshl_b32 s0, s1, 5
	s_mov_b64 s[14:15], 0x80
	s_and_b32 s18, s0, 0x60
	s_add_i32 m0, s21, 0x18000
	v_lshl_add_u64 v[2:3], v[2:3], 0, s[14:15]
	s_lshl_b32 s17, s18, 7
	s_waitcnt vmcnt(2)
	s_barrier
	global_load_lds_dwordx4 v[2:3], off
	v_lshl_add_u64 v[2:3], v[4:5], 0, s[14:15]
	s_add_i32 m0, s21, 0x1a000
	s_add_i32 s64, s21, 0x8000
	s_add_i32 s65, s21, 0xa000
	global_load_lds_dwordx4 v[2:3], off
	v_lshl_add_u64 v[2:3], v[6:7], 0, s[14:15]
	s_mov_b32 m0, s64
	s_add_u32 s0, s54, 0x80080
	global_load_lds_dwordx4 v[2:3], off
	v_lshl_add_u64 v[2:3], v[8:9], 0, s[14:15]
	s_mov_b32 m0, s65
	s_addc_u32 s1, s55, 0
	global_load_lds_dwordx4 v[2:3], off
	v_lshl_add_u64 v[2:3], s[0:1], 0, v[132:133]
	s_add_i32 m0, s21, 0x1c000
	v_lshl_add_u64 v[2:3], v[2:3], 0, v[130:131]
	global_load_lds_dwordx4 v[2:3], off
	v_lshl_add_u64 v[2:3], s[0:1], 0, v[136:137]
	v_lshl_add_u64 v[2:3], v[2:3], 0, v[130:131]
	s_add_i32 m0, s21, 0x1e000
	v_lshlrev_b32_e32 v5, 2, v178
	global_load_lds_dwordx4 v[2:3], off
	v_add_u32_e32 v132, v132, v130
	v_add_u32_e32 v136, v136, v130
	v_add_u32_e32 v138, v138, v130
	v_add_u32_e32 v140, v140, v130
	v_and_b32_e32 v2, 3, v176
	v_lshlrev_b32_e32 v4, 4, v2
	v_lshl_or_b32 v3, v178, 6, v4
	v_and_b32_e32 v5, 32, v5
	v_bitop3_b32 v5, v3, s16, v5 bitop3:0xde
	v_lshlrev_b32_e32 v3, 6, v0
	s_movk_i32 s0, 0x3c0
	v_and_or_b32 v3, v3, s0, v4
	v_and_b32_e32 v6, 32, v177
	v_lshlrev_b32_e32 v134, 5, v178
	v_bitop3_b32 v179, s17, v3, v6 bitop3:0xf6
	s_cmpk_lt_u32 s12, 0x100
	v_lshl_or_b32 v142, v2, 3, s18
	v_cmp_eq_u32_e64 s[0:1], 0, v2
	v_lshl_add_u64 v[2:3], s[86:87], 0, v[134:135]
	v_and_b32_e32 v134, 16, v4
	s_cselect_b64 s[16:17], -1, 0
	s_add_u32 s66, s86, 0x10300000
	v_lshl_add_u64 v[2:3], v[2:3], 0, v[134:135]
	s_mov_b64 s[28:29], 0x6600000
	s_addc_u32 s67, s87, 0
	v_lshl_add_u64 v[144:145], v[2:3], 0, s[28:29]
	v_lshlrev_b32_e32 v2, 9, v0
	s_add_u32 s68, s86, 0x400000
	v_and_b32_e32 v2, 0x30000, v2
	v_lshlrev_b32_e32 v3, 12, v10
	v_add_u32_e32 v4, v11, v12
	s_addc_u32 s69, s87, 0
	v_or3_b32 v134, v2, v3, v4
	v_lshlrev_b32_e32 v2, 5, v13
	s_mov_b64 s[22:23], 0x80080
	s_waitcnt vmcnt(6)
	s_add_u32 s18, s86, 0x100000
	v_and_b32_e32 v2, 0x70000, v2
	s_addc_u32 s19, s87, 0
	v_lshl_add_u64 v[146:147], v[134:135], 0, s[22:23]
	v_or3_b32 v134, v2, v3, v4
	s_add_i32 s71, 0, 0x10000
	s_add_i32 s72, 0, 0x14000
	v_mbcnt_lo_u32_b32 v2, -1, 0
	v_mov_b32_e32 v143, v135
	v_or_b32_e32 v180, 0xfffffc00, v142
	v_or_b32_e32 v181, 0xfffffc80, v142
	v_lshl_add_u64 v[148:149], v[134:135], 0, s[22:23]
	s_movk_i32 s70, 0x300
	v_add_u32_e32 v182, s71, v179
	v_add_u32_e32 v183, s72, v179
	v_add_u32_e32 v184, 0, v5
	s_mov_b32 s20, 0x437f0000
	s_movk_i32 s73, 0xfc
	s_mov_b32 s74, 0x7e00000
	s_mov_b32 s75, 0x20000
	s_movk_i32 s76, 0xfd
	s_movk_i32 s77, 0xfe
	s_movk_i32 s78, 0xff
	v_mbcnt_hi_u32_b32 v185, -1, v2
	s_mov_b32 s79, 0
	s_mov_b64 s[36:37], s[54:55]
	s_mov_b64 s[28:29], s[6:7]
	s_barrier
	s_branch .LBB0_243

; #define PG8_STAGE(bufoff, gbase, RR, ld) do { _Pragma("unroll") for (int _i = 0; _i < 2; ++_i) \
;         __builtin_amdgcn_global_load_lds((const unsigned*)((const char*)(gbase) + (RR)[_i] * (ld) + C2[_i]), (LAS unsigned*)(lds + (bufoff) + ldsw + _i * 8192), 16, 0, 0); } while (0)
; #define PG8_LDA(dst, b, h) do { _Pragma("unroll") for (int m = 0; m < 4; ++m) _Pragma("unroll") for (int k = 0; k < 2; ++k) dst[m][k] = *(const LAS bf16x8*)(lds + PG8_SA(b, h) + aoff + m * 2048 + k * 1024); } while (0)
; #define PG8_LDB(dst, b, h) do { _Pragma("unroll") for (int n = 0; n < 2; ++n) _Pragma("unroll") for (int k = 0; k < 2; ++k) dst[n][k] = *(const LAS bf16x8*)(lds + PG8_SB(b, h) + boff + n * 2048 + k * 1024); } while (0)
; #define PG8_WAIT_V(n) asm volatile("s_waitcnt vmcnt(" #n ")" ::: "memory")
; #define PG8_WAIT_L(n) asm volatile("s_waitcnt lgkmcnt(" #n ")" ::: "memory")
; #define PG8_BAR __builtin_amdgcn_s_barrier()
; #define PG8_SCHED __builtin_amdgcn_sched_barrier(0)
; template <class Sched, class Epi>
; __device__ __forceinline__ void gemm_run(LAS unsigned char* lds, const Sched& S, const Epi& E) {
;     ...
;         const bool has_next = S.next(ui + 1, nxt);
;         const char* nA = has_next ? nxt.A : cA; const char* nB = has_next ? nxt.B : cB; const unsigned nlda = has_next ? nxt.lda : lda, nldb = has_next ? nxt.ldb : ldb;
;         const int nt = cur.nt;
;         for (int t = 0; t < nt; t += 2) {
;             const bool last = (t == nt - 2);
;             const char* a1 = cA + (size_t)(t + 1) * kstep;
;             const char* a2 = last ? nA : cA + (size_t)(t + 2) * kstep; const char* b2 = last ? nB : cB + (size_t)(t + 2) * kstep;
;             const unsigned la2 = last ? nlda : lda, lb2 = last ? nldb : ldb;
;             const char* a3 = a2 + kstep; const char* b3 = b2 + kstep;
;             PG8_LDB(B0, 0, 0); PG8_LDB(B1, 0, 1); PG8_SCHED; PG8_LDA(At, 0, 0); PG8_STAGE(PG8_SA(1, 1), a1 + (size_t)HALF * lda, RA, lda);
;             PG8_WAIT_V(8); PG8_WAIT_L(0); PG8_BAR; PG8_MMA(0, 0, At, B0); PG8_MMA(0, 1, At, B1); PG8_BAR; PG8_SCHED;
;             PG8_LDA(At, 0, 1); PG8_STAGE(PG8_SB(0, 0), b2, RB, lb2); PG8_STAGE(PG8_SB(0, 1), b2 + (size_t)HALF * lb2, RB, lb2); PG8_STAGE(PG8_SA(0, 0), a2, RA, la2);
;             PG8_WAIT_V(8); PG8_WAIT_L(0); PG8_BAR; PG8_MMA(1, 0, At, B0); PG8_MMA(1, 1, At, B1); PG8_BAR; PG8_SCHED;
.LBB0_245:
	s_add_u32 s12, s54, 0x100
	s_addc_u32 s33, s55, 0
	s_mov_b32 s38, -2
	s_mov_b64 s[54:55], 0
	s_waitcnt lgkmcnt(0)
	s_waitcnt vmcnt(0)
	ds_read_b128 v[154:157], v182
	ds_read_b128 v[158:161], v182 offset:1024
	ds_read_b128 v[162:165], v182 offset:2048
	ds_read_b128 v[166:169], v182 offset:3072
	ds_read_b128 v[170:173], v183
	ds_read_b128 v[186:189], v183 offset:1024
	ds_read_b128 v[190:193], v183 offset:2048
	ds_read_b128 v[194:197], v183 offset:3072
	s_add_u32 s39, s6, s54
	s_addc_u32 s40, s7, s55
	s_mov_b32 s98, s39
	s_mov_b32 s99, s40
	s_add_u32 s39, s39, 0x100
	s_addc_u32 s40, s40, 0
	s_add_u32 s41, s12, s54
	s_addc_u32 s42, s33, s55
	s_cmpk_eq_i32 s54, 0xf00
	s_cselect_b32 s59, s29, s40
	s_cselect_b32 s58, s28, s39
	s_cselect_b32 s57, s37, s42
	s_cselect_b32 s56, s36, s41
	s_add_i32 m0, s21, 0xc000
	ds_read_b128 v[198:201], v184
	ds_read_b128 v[202:205], v184 offset:1024
	ds_read_b128 v[206:209], v184 offset:2048
	ds_read_b128 v[210:213], v184 offset:3072
	ds_read_b128 v[214:217], v184 offset:4096
	ds_read_b128 v[218:221], v184 offset:5120
	ds_read_b128 v[222:225], v184 offset:6144
	ds_read_b128 v[226:229], v184 offset:7168
	global_load_lds_dwordx4 v146, s[98:99]
	s_add_i32 m0, s21, 0xe000
	s_nop 0
	global_load_lds_dwordx4 v148, s[98:99]
	s_waitcnt vmcnt(8)
	s_waitcnt lgkmcnt(0)
	s_barrier
	s_waitcnt lgkmcnt(0)
	v_mfma_f32_16x16x32_bf16 v[126:129], v[154:157], v[198:201], 0
	v_mfma_f32_16x16x32_bf16 v[122:125], v[162:165], v[198:201], 0
	v_mfma_f32_16x16x32_bf16 v[110:113], v[154:157], v[206:209], 0
	v_mfma_f32_16x16x32_bf16 v[106:109], v[162:165], v[206:209], 0
	v_mfma_f32_16x16x32_bf16 v[94:97], v[154:157], v[214:217], 0
	v_mfma_f32_16x16x32_bf16 v[90:93], v[162:165], v[214:217], 0
	v_mfma_f32_16x16x32_bf16 v[78:81], v[154:157], v[222:225], 0
	v_mfma_f32_16x16x32_bf16 v[74:77], v[162:165], v[222:225], 0
	v_mfma_f32_16x16x32_bf16 v[126:129], v[158:161], v[202:205], v[126:129]
	v_mfma_f32_16x16x32_bf16 v[122:125], v[166:169], v[202:205], v[122:125]
	v_mfma_f32_16x16x32_bf16 v[110:113], v[158:161], v[210:213], v[110:113]
	v_mfma_f32_16x16x32_bf16 v[106:109], v[166:169], v[210:213], v[106:109]
	v_mfma_f32_16x16x32_bf16 v[94:97], v[158:161], v[218:221], v[94:97]
	v_mfma_f32_16x16x32_bf16 v[90:93], v[166:169], v[218:221], v[90:93]
	v_mfma_f32_16x16x32_bf16 v[78:81], v[158:161], v[226:229], v[78:81]
	v_mfma_f32_16x16x32_bf16 v[74:77], v[166:169], v[226:229], v[74:77]
	v_mfma_f32_16x16x32_bf16 v[118:121], v[170:173], v[198:201], 0
	v_mfma_f32_16x16x32_bf16 v[114:117], v[190:193], v[198:201], 0
	v_mfma_f32_16x16x32_bf16 v[102:105], v[170:173], v[206:209], 0
	v_mfma_f32_16x16x32_bf16 v[98:101], v[190:193], v[206:209], 0
	v_mfma_f32_16x16x32_bf16 v[86:89], v[170:173], v[214:217], 0
	v_mfma_f32_16x16x32_bf16 v[82:85], v[190:193], v[214:217], 0
	v_mfma_f32_16x16x32_bf16 v[70:73], v[170:173], v[222:225], 0
	v_mfma_f32_16x16x32_bf16 v[66:69], v[190:193], v[222:225], 0
	v_mfma_f32_16x16x32_bf16 v[118:121], v[186:189], v[202:205], v[118:121]
	v_mfma_f32_16x16x32_bf16 v[114:117], v[194:197], v[202:205], v[114:117]
	v_mfma_f32_16x16x32_bf16 v[102:105], v[186:189], v[210:213], v[102:105]
	v_mfma_f32_16x16x32_bf16 v[98:101], v[194:197], v[210:213], v[98:101]
	v_mfma_f32_16x16x32_bf16 v[86:89], v[186:189], v[218:221], v[86:89]
	v_mfma_f32_16x16x32_bf16 v[82:85], v[194:197], v[218:221], v[82:85]
	v_mfma_f32_16x16x32_bf16 v[70:73], v[186:189], v[226:229], v[70:73]
	v_mfma_f32_16x16x32_bf16 v[66:69], v[194:197], v[226:229], v[66:69]
	s_barrier
	s_add_i32 s39, s71, s3
	s_mov_b32 m0, s39
	ds_read_b128 v[198:201], v184 offset:16384
	ds_read_b128 v[202:205], v184 offset:17408
	ds_read_b128 v[206:209], v184 offset:18432
	ds_read_b128 v[210:213], v184 offset:19456
	ds_read_b128 v[214:217], v184 offset:20480
	ds_read_b128 v[218:221], v184 offset:21504
	ds_read_b128 v[222:225], v184 offset:22528
	ds_read_b128 v[226:229], v184 offset:23552
	global_load_lds_dwordx4 v132, s[56:57]
	s_add_i32 m0, s39, 0x2000
	s_add_u32 s40, s56, 0x80000
	s_addc_u32 s41, s57, 0
	s_add_i32 s39, s72, s3
	global_load_lds_dwordx4 v136, s[56:57]
	s_mov_b32 m0, s39
	s_nop 0
	global_load_lds_dwordx4 v132, s[40:41]
	s_add_i32 m0, s39, 0x2000
	s_nop 0
	global_load_lds_dwordx4 v136, s[40:41]
	s_mov_b32 m0, s21
	s_nop 0
	global_load_lds_dwordx4 v138, s[58:59]
	s_mov_b32 m0, s35
	s_nop 0
	global_load_lds_dwordx4 v140, s[58:59]
	s_waitcnt vmcnt(8)
	s_waitcnt lgkmcnt(0)
	s_barrier
	s_waitcnt lgkmcnt(0)
	v_mfma_f32_16x16x32_bf16 v[62:65], v[154:157], v[198:201], 0
	v_mfma_f32_16x16x32_bf16 v[58:61], v[162:165], v[198:201], 0
	v_mfma_f32_16x16x32_bf16 v[46:49], v[154:157], v[206:209], 0
	v_mfma_f32_16x16x32_bf16 v[42:45], v[162:165], v[206:209], 0
	v_mfma_f32_16x16x32_bf16 v[30:33], v[154:157], v[214:217], 0
	v_mfma_f32_16x16x32_bf16 v[26:29], v[162:165], v[214:217], 0
	v_mfma_f32_16x16x32_bf16 v[14:17], v[154:157], v[222:225], 0
	v_mfma_f32_16x16x32_bf16 v[10:13], v[162:165], v[222:225], 0
	v_mfma_f32_16x16x32_bf16 v[62:65], v[158:161], v[202:205], v[62:65]
	v_mfma_f32_16x16x32_bf16 v[58:61], v[166:169], v[202:205], v[58:61]
	v_mfma_f32_16x16x32_bf16 v[46:49], v[158:161], v[210:213], v[46:49]
	v_mfma_f32_16x16x32_bf16 v[42:45], v[166:169], v[210:213], v[42:45]
	v_mfma_f32_16x16x32_bf16 v[30:33], v[158:161], v[218:221], v[30:33]
	v_mfma_f32_16x16x32_bf16 v[26:29], v[166:169], v[218:221], v[26:29]
	v_mfma_f32_16x16x32_bf16 v[14:17], v[158:161], v[226:229], v[14:17]
	v_mfma_f32_16x16x32_bf16 v[10:13], v[166:169], v[226:229], v[10:13]
	v_mfma_f32_16x16x32_bf16 v[54:57], v[170:173], v[198:201], 0
	v_mfma_f32_16x16x32_bf16 v[50:53], v[190:193], v[198:201], 0
	v_mfma_f32_16x16x32_bf16 v[38:41], v[170:173], v[206:209], 0
	v_mfma_f32_16x16x32_bf16 v[34:37], v[190:193], v[206:209], 0
	v_mfma_f32_16x16x32_bf16 v[22:25], v[170:173], v[214:217], 0
	v_mfma_f32_16x16x32_bf16 v[18:21], v[190:193], v[214:217], 0
	v_mfma_f32_16x16x32_bf16 v[6:9], v[170:173], v[222:225], 0
	v_mfma_f32_16x16x32_bf16 v[2:5], v[190:193], v[222:225], 0
	v_mfma_f32_16x16x32_bf16 v[54:57], v[186:189], v[202:205], v[54:57]
	v_mfma_f32_16x16x32_bf16 v[50:53], v[194:197], v[202:205], v[50:53]
	v_mfma_f32_16x16x32_bf16 v[38:41], v[186:189], v[210:213], v[38:41]
	v_mfma_f32_16x16x32_bf16 v[34:37], v[194:197], v[210:213], v[34:37]
	v_mfma_f32_16x16x32_bf16 v[22:25], v[186:189], v[218:221], v[22:25]
	v_mfma_f32_16x16x32_bf16 v[18:21], v[194:197], v[218:221], v[18:21]
	v_mfma_f32_16x16x32_bf16 v[6:9], v[186:189], v[226:229], v[6:9]
	v_mfma_f32_16x16x32_bf16 v[2:5], v[194:197], v[226:229], v[2:5]
	s_barrier
; #define PG8_STAGE(bufoff, gbase, RR, ld) do { _Pragma("unroll") for (int _i = 0; _i < 2; ++_i) \
;         __builtin_amdgcn_global_load_lds((const unsigned*)((const char*)(gbase) + (RR)[_i] * (ld) + C2[_i]), (LAS unsigned*)(lds + (bufoff) + ldsw + _i * 8192), 16, 0, 0); } while (0)
; #define PG8_LDA(dst, b, h) do { _Pragma("unroll") for (int m = 0; m < 4; ++m) _Pragma("unroll") for (int k = 0; k < 2; ++k) dst[m][k] = *(const LAS bf16x8*)(lds + PG8_SA(b, h) + aoff + m * 2048 + k * 1024); } while (0)
; #define PG8_LDB(dst, b, h) do { _Pragma("unroll") for (int n = 0; n < 2; ++n) _Pragma("unroll") for (int k = 0; k < 2; ++k) dst[n][k] = *(const LAS bf16x8*)(lds + PG8_SB(b, h) + boff + n * 2048 + k * 1024); } while (0)
; template <class Sched, class Epi>
; __device__ __forceinline__ void gemm_run(LAS unsigned char* lds, const Sched& S, const Epi& E) {
;     ...
;         for (int t = 0; t < nt; t += 2) {
;             const bool last = (t == nt - 2);
;             const char* a1 = cA + (size_t)(t + 1) * kstep;
;             const char* a2 = last ? nA : cA + (size_t)(t + 2) * kstep; const char* b2 = last ? nB : cB + (size_t)(t + 2) * kstep;
;             const unsigned la2 = last ? nlda : lda, lb2 = last ? nldb : ldb;
;             const char* a3 = a2 + kstep; const char* b3 = b2 + kstep;
;             PG8_LDB(B0, 0, 0); PG8_LDB(B1, 0, 1); PG8_SCHED; PG8_LDA(At, 0, 0); PG8_STAGE(PG8_SA(1, 1), a1 + (size_t)HALF * lda, RA, lda);
;             PG8_WAIT_V(8); PG8_WAIT_L(0); PG8_BAR; PG8_MMA(0, 0, At, B0); PG8_MMA(0, 1, At, B1); PG8_BAR; PG8_SCHED;
;             PG8_LDA(At, 0, 1); PG8_STAGE(PG8_SB(0, 0), b2, RB, lb2); PG8_STAGE(PG8_SB(0, 1), b2 + (size_t)HALF * lb2, RB, lb2); PG8_STAGE(PG8_SA(0, 0), a2, RA, la2);
;             PG8_WAIT_V(8); PG8_WAIT_L(0); PG8_BAR; PG8_MMA(1, 0, At, B0); PG8_MMA(1, 1, At, B1); PG8_BAR; PG8_SCHED;
;             PG8_LDB(B0, 1, 0); PG8_LDB(B1, 1, 1); PG8_SCHED; PG8_LDA(At, 1, 0); PG8_STAGE(PG8_SA(0, 1), a2 + (size_t)HALF * la2, RA, la2);
;             PG8_WAIT_V(8); PG8_WAIT_L(0); PG8_BAR; PG8_MMA(0, 0, At, B0); PG8_MMA(0, 1, At, B1); PG8_BAR; PG8_SCHED;
;             PG8_LDA(At, 1, 1); PG8_STAGE(PG8_SB(1, 0), b3, RB, lb2); PG8_STAGE(PG8_SB(1, 1), b3 + (size_t)HALF * lb2, RB, lb2); PG8_STAGE(PG8_SA(1, 0), a3, RA, la2);
;             PG8_WAIT_V(8); PG8_WAIT_L(0); PG8_BAR; PG8_MMA(1, 0, At, B0); PG8_MMA(1, 1, At, B1); PG8_BAR; PG8_SCHED;
	s_add_i32 s39, 0, 0x18000
	v_add_u32_e32 v134, s39, v179
	s_add_i32 s42, 0, 0x1c000
	ds_read_b128 v[154:157], v134
	ds_read_b128 v[158:161], v134 offset:1024
	ds_read_b128 v[162:165], v134 offset:2048
	ds_read_b128 v[166:169], v134 offset:3072
	v_add_u32_e32 v134, s42, v179
	ds_read_b128 v[170:173], v134
	ds_read_b128 v[186:189], v134 offset:1024
	ds_read_b128 v[190:193], v134 offset:2048
	ds_read_b128 v[194:197], v134 offset:3072
	s_add_u32 s40, s58, 0x80000
	s_addc_u32 s41, s59, 0
	s_mov_b32 m0, s60
	ds_read_b128 v[198:201], v184 offset:32768
	ds_read_b128 v[202:205], v184 offset:33792
	ds_read_b128 v[206:209], v184 offset:34816
	ds_read_b128 v[210:213], v184 offset:35840
	ds_read_b128 v[214:217], v184 offset:36864
	ds_read_b128 v[218:221], v184 offset:37888
	ds_read_b128 v[222:225], v184 offset:38912
	ds_read_b128 v[226:229], v184 offset:39936
	global_load_lds_dwordx4 v138, s[40:41]
	s_mov_b32 m0, s61
	s_nop 0
	global_load_lds_dwordx4 v140, s[40:41]
	s_waitcnt vmcnt(8)
	s_waitcnt lgkmcnt(0)
	s_barrier
	s_waitcnt lgkmcnt(0)
	v_mfma_f32_16x16x32_bf16 v[126:129], v[154:157], v[198:201], v[126:129]
	v_mfma_f32_16x16x32_bf16 v[122:125], v[162:165], v[198:201], v[122:125]
	v_mfma_f32_16x16x32_bf16 v[110:113], v[154:157], v[206:209], v[110:113]
	v_mfma_f32_16x16x32_bf16 v[106:109], v[162:165], v[206:209], v[106:109]
	v_mfma_f32_16x16x32_bf16 v[94:97], v[154:157], v[214:217], v[94:97]
	v_mfma_f32_16x16x32_bf16 v[90:93], v[162:165], v[214:217], v[90:93]
	v_mfma_f32_16x16x32_bf16 v[78:81], v[154:157], v[222:225], v[78:81]
	v_mfma_f32_16x16x32_bf16 v[74:77], v[162:165], v[222:225], v[74:77]
	v_mfma_f32_16x16x32_bf16 v[126:129], v[158:161], v[202:205], v[126:129]
	v_mfma_f32_16x16x32_bf16 v[122:125], v[166:169], v[202:205], v[122:125]
	v_mfma_f32_16x16x32_bf16 v[110:113], v[158:161], v[210:213], v[110:113]
	v_mfma_f32_16x16x32_bf16 v[106:109], v[166:169], v[210:213], v[106:109]
	v_mfma_f32_16x16x32_bf16 v[94:97], v[158:161], v[218:221], v[94:97]
	v_mfma_f32_16x16x32_bf16 v[90:93], v[166:169], v[218:221], v[90:93]
	v_mfma_f32_16x16x32_bf16 v[78:81], v[158:161], v[226:229], v[78:81]
	v_mfma_f32_16x16x32_bf16 v[74:77], v[166:169], v[226:229], v[74:77]
	v_mfma_f32_16x16x32_bf16 v[118:121], v[170:173], v[198:201], v[118:121]
	v_mfma_f32_16x16x32_bf16 v[114:117], v[190:193], v[198:201], v[114:117]
	v_mfma_f32_16x16x32_bf16 v[102:105], v[170:173], v[206:209], v[102:105]
	v_mfma_f32_16x16x32_bf16 v[98:101], v[190:193], v[206:209], v[98:101]
	v_mfma_f32_16x16x32_bf16 v[86:89], v[170:173], v[214:217], v[86:89]
	v_mfma_f32_16x16x32_bf16 v[82:85], v[190:193], v[214:217], v[82:85]
	v_mfma_f32_16x16x32_bf16 v[70:73], v[170:173], v[222:225], v[70:73]
	v_mfma_f32_16x16x32_bf16 v[66:69], v[190:193], v[222:225], v[66:69]
	v_mfma_f32_16x16x32_bf16 v[118:121], v[186:189], v[202:205], v[118:121]
	v_mfma_f32_16x16x32_bf16 v[114:117], v[194:197], v[202:205], v[114:117]
	v_mfma_f32_16x16x32_bf16 v[102:105], v[186:189], v[210:213], v[102:105]
	v_mfma_f32_16x16x32_bf16 v[98:101], v[194:197], v[210:213], v[98:101]
	v_mfma_f32_16x16x32_bf16 v[86:89], v[186:189], v[218:221], v[86:89]
	v_mfma_f32_16x16x32_bf16 v[82:85], v[194:197], v[218:221], v[82:85]
	v_mfma_f32_16x16x32_bf16 v[70:73], v[186:189], v[226:229], v[70:73]
	v_mfma_f32_16x16x32_bf16 v[66:69], v[194:197], v[226:229], v[66:69]
	s_barrier
	s_add_i32 s39, s39, s3
	s_mov_b32 m0, s39
	ds_read_b128 v[198:201], v184 offset:49152
	ds_read_b128 v[202:205], v184 offset:50176
	ds_read_b128 v[206:209], v184 offset:51200
	ds_read_b128 v[210:213], v184 offset:52224
	ds_read_b128 v[214:217], v184 offset:53248
	ds_read_b128 v[218:221], v184 offset:54272
	ds_read_b128 v[222:225], v184 offset:55296
	ds_read_b128 v[226:229], v184 offset:56320
	s_add_u32 s98, s56, 0x80
	s_addc_u32 s99, s57, 0
	global_load_lds_dwordx4 v132, s[98:99]
	s_add_i32 m0, s39, 0x2000
	s_add_u32 s40, s56, 0x80080
	s_addc_u32 s41, s57, 0
	global_load_lds_dwordx4 v136, s[98:99]
	s_add_i32 s39, s42, s3
	s_mov_b32 m0, s39
	s_nop 0
	global_load_lds_dwordx4 v132, s[40:41]
	s_add_i32 m0, s39, 0x2000
	s_nop 0
	global_load_lds_dwordx4 v136, s[40:41]
	s_mov_b32 m0, s64
	s_nop 0
	s_add_u32 s100, s58, 0x80
	s_addc_u32 s101, s59, 0
	global_load_lds_dwordx4 v138, s[100:101]
	s_mov_b32 m0, s65
	s_nop 0
	global_load_lds_dwordx4 v140, s[100:101]
	s_waitcnt vmcnt(8)
	s_waitcnt lgkmcnt(0)
	s_barrier
	s_waitcnt lgkmcnt(0)
	v_mfma_f32_16x16x32_bf16 v[62:65], v[154:157], v[198:201], v[62:65]
	v_mfma_f32_16x16x32_bf16 v[58:61], v[162:165], v[198:201], v[58:61]
	v_mfma_f32_16x16x32_bf16 v[46:49], v[154:157], v[206:209], v[46:49]
	v_mfma_f32_16x16x32_bf16 v[42:45], v[162:165], v[206:209], v[42:45]
	v_mfma_f32_16x16x32_bf16 v[30:33], v[154:157], v[214:217], v[30:33]
	v_mfma_f32_16x16x32_bf16 v[26:29], v[162:165], v[214:217], v[26:29]
	v_mfma_f32_16x16x32_bf16 v[14:17], v[154:157], v[222:225], v[14:17]
	v_mfma_f32_16x16x32_bf16 v[10:13], v[162:165], v[222:225], v[10:13]
	v_mfma_f32_16x16x32_bf16 v[62:65], v[158:161], v[202:205], v[62:65]
	v_mfma_f32_16x16x32_bf16 v[58:61], v[166:169], v[202:205], v[58:61]
	v_mfma_f32_16x16x32_bf16 v[46:49], v[158:161], v[210:213], v[46:49]
	v_mfma_f32_16x16x32_bf16 v[42:45], v[166:169], v[210:213], v[42:45]
	v_mfma_f32_16x16x32_bf16 v[30:33], v[158:161], v[218:221], v[30:33]
	v_mfma_f32_16x16x32_bf16 v[26:29], v[166:169], v[218:221], v[26:29]
	v_mfma_f32_16x16x32_bf16 v[14:17], v[158:161], v[226:229], v[14:17]
	v_mfma_f32_16x16x32_bf16 v[10:13], v[166:169], v[226:229], v[10:13]
	v_mfma_f32_16x16x32_bf16 v[54:57], v[170:173], v[198:201], v[54:57]
	v_mfma_f32_16x16x32_bf16 v[50:53], v[190:193], v[198:201], v[50:53]
	v_mfma_f32_16x16x32_bf16 v[38:41], v[170:173], v[206:209], v[38:41]
	v_mfma_f32_16x16x32_bf16 v[34:37], v[190:193], v[206:209], v[34:37]
	v_mfma_f32_16x16x32_bf16 v[22:25], v[170:173], v[214:217], v[22:25]
	v_mfma_f32_16x16x32_bf16 v[18:21], v[190:193], v[214:217], v[18:21]
	v_mfma_f32_16x16x32_bf16 v[6:9], v[170:173], v[222:225], v[6:9]
	v_mfma_f32_16x16x32_bf16 v[2:5], v[190:193], v[222:225], v[2:5]
	v_mfma_f32_16x16x32_bf16 v[54:57], v[186:189], v[202:205], v[54:57]
	v_mfma_f32_16x16x32_bf16 v[50:53], v[194:197], v[202:205], v[50:53]
	v_mfma_f32_16x16x32_bf16 v[38:41], v[186:189], v[210:213], v[38:41]
	v_mfma_f32_16x16x32_bf16 v[34:37], v[194:197], v[210:213], v[34:37]
	v_mfma_f32_16x16x32_bf16 v[22:25], v[186:189], v[218:221], v[22:25]
	v_mfma_f32_16x16x32_bf16 v[18:21], v[194:197], v[218:221], v[18:21]
	v_mfma_f32_16x16x32_bf16 v[6:9], v[186:189], v[226:229], v[6:9]
	v_mfma_f32_16x16x32_bf16 v[2:5], v[194:197], v[226:229], v[2:5]
	s_barrier
	s_add_i32 s38, s38, 2
	s_add_u32 s54, s54, 0x100
	s_addc_u32 s55, s55, 0
	s_cmp_gt_u32 s38, 29
	s_cbranch_scc0 .LBB0_246
	.p2align 6
; #define PG8_STAGE(bufoff, gbase, RR, ld) do { _Pragma("unroll") for (int _i = 0; _i < 2; ++_i) \
;         __builtin_amdgcn_global_load_lds((const unsigned*)((const char*)(gbase) + (RR)[_i] * (ld) + C2[_i]), (LAS unsigned*)(lds + (bufoff) + ldsw + _i * 8192), 16, 0, 0); } while (0)
; #define PG8_LDA(dst, b, h) do { _Pragma("unroll") for (int m = 0; m < 4; ++m) _Pragma("unroll") for (int k = 0; k < 2; ++k) dst[m][k] = *(const LAS bf16x8*)(lds + PG8_SA(b, h) + aoff + m * 2048 + k * 1024); } while (0)
; #define PG8_LDB(dst, b, h) do { _Pragma("unroll") for (int n = 0; n < 2; ++n) _Pragma("unroll") for (int k = 0; k < 2; ++k) dst[n][k] = *(const LAS bf16x8*)(lds + PG8_SB(b, h) + boff + n * 2048 + k * 1024); } while (0)
; #define PG8_MMA(ai, bj, At, Bt) do { __builtin_amdgcn_s_setprio(1); _Pragma("unroll") for (int m = 0; m < 4; ++m) _Pragma("unroll") for (int n = 0; n < 2; ++n) _Pragma("unroll") for (int k = 0; k < 2; ++k) \
;         acc[ai][bj][m][n] = __builtin_amdgcn_mfma_f32_16x16x32_bf16(Bt[n][k], At[m][k], acc[ai][bj][m][n], 0, 0, 0); __builtin_amdgcn_s_setprio(0); } while (0)
; #define PG8_WAIT_V(n) asm volatile("s_waitcnt vmcnt(" #n ")" ::: "memory")
; #define PG8_WAIT_L(n) asm volatile("s_waitcnt lgkmcnt(" #n ")" ::: "memory")
; template <class Sched, class Epi>
; __device__ __forceinline__ void gemm_run(LAS unsigned char* lds, const Sched& S, const Epi& E) {
;     ...
;         for (int t = 0; t < nt; t += 2) {
;             const bool last = (t == nt - 2);
;             const char* a1 = cA + (size_t)(t + 1) * kstep;
;             const char* a2 = last ? nA : cA + (size_t)(t + 2) * kstep; const char* b2 = last ? nB : cB + (size_t)(t + 2) * kstep;
;             const unsigned la2 = last ? nlda : lda, lb2 = last ? nldb : ldb;
;             const char* a3 = a2 + kstep; const char* b3 = b2 + kstep;
;             PG8_LDB(B0, 0, 0); PG8_LDB(B1, 0, 1); PG8_SCHED; PG8_LDA(At, 0, 0); PG8_STAGE(PG8_SA(1, 1), a1 + (size_t)HALF * lda, RA, lda);
;             PG8_WAIT_V(8); PG8_WAIT_L(0); PG8_BAR; PG8_MMA(0, 0, At, B0); PG8_MMA(0, 1, At, B1); PG8_BAR; PG8_SCHED;
;             PG8_LDA(At, 0, 1); PG8_STAGE(PG8_SB(0, 0), b2, RB, lb2); PG8_STAGE(PG8_SB(0, 1), b2 + (size_t)HALF * lb2, RB, lb2); PG8_STAGE(PG8_SA(0, 0), a2, RA, la2);
;             PG8_WAIT_V(8); PG8_WAIT_L(0); PG8_BAR; PG8_MMA(1, 0, At, B0); PG8_MMA(1, 1, At, B1); PG8_BAR; PG8_SCHED;
.LBB0_246:
	ds_read_b128 v[154:157], v182
	ds_read_b128 v[158:161], v182 offset:1024
	ds_read_b128 v[162:165], v182 offset:2048
	ds_read_b128 v[166:169], v182 offset:3072
	ds_read_b128 v[170:173], v183
	ds_read_b128 v[186:189], v183 offset:1024
	ds_read_b128 v[190:193], v183 offset:2048
	ds_read_b128 v[194:197], v183 offset:3072
	s_add_u32 s39, s6, s54
	s_addc_u32 s40, s7, s55
	s_mov_b32 s98, s39
	s_mov_b32 s99, s40
	s_add_u32 s39, s39, 0x100
	s_addc_u32 s40, s40, 0
	s_add_u32 s41, s12, s54
	s_addc_u32 s42, s33, s55
	s_cmpk_eq_i32 s54, 0xf00
	s_cselect_b32 s59, s29, s40
	s_cselect_b32 s58, s28, s39
	s_cselect_b32 s57, s37, s42
	s_cselect_b32 s56, s36, s41
	s_add_i32 m0, s21, 0xc000
	ds_read_b128 v[198:201], v184
	ds_read_b128 v[202:205], v184 offset:1024
	ds_read_b128 v[206:209], v184 offset:2048
	ds_read_b128 v[210:213], v184 offset:3072
	ds_read_b128 v[214:217], v184 offset:4096
	ds_read_b128 v[218:221], v184 offset:5120
	ds_read_b128 v[222:225], v184 offset:6144
	ds_read_b128 v[226:229], v184 offset:7168
	global_load_lds_dwordx4 v146, s[98:99]
	s_add_i32 m0, s21, 0xe000
	s_nop 0
	global_load_lds_dwordx4 v148, s[98:99]
	s_waitcnt vmcnt(8)
	s_waitcnt lgkmcnt(0)
	s_barrier
	s_waitcnt lgkmcnt(0)
	v_mfma_f32_16x16x32_bf16 v[126:129], v[154:157], v[198:201], v[126:129]
	v_mfma_f32_16x16x32_bf16 v[122:125], v[162:165], v[198:201], v[122:125]
	v_mfma_f32_16x16x32_bf16 v[110:113], v[154:157], v[206:209], v[110:113]
	v_mfma_f32_16x16x32_bf16 v[106:109], v[162:165], v[206:209], v[106:109]
	v_mfma_f32_16x16x32_bf16 v[94:97], v[154:157], v[214:217], v[94:97]
	v_mfma_f32_16x16x32_bf16 v[90:93], v[162:165], v[214:217], v[90:93]
	v_mfma_f32_16x16x32_bf16 v[78:81], v[154:157], v[222:225], v[78:81]
	v_mfma_f32_16x16x32_bf16 v[74:77], v[162:165], v[222:225], v[74:77]
	v_mfma_f32_16x16x32_bf16 v[126:129], v[158:161], v[202:205], v[126:129]
	v_mfma_f32_16x16x32_bf16 v[122:125], v[166:169], v[202:205], v[122:125]
	v_mfma_f32_16x16x32_bf16 v[110:113], v[158:161], v[210:213], v[110:113]
	v_mfma_f32_16x16x32_bf16 v[106:109], v[166:169], v[210:213], v[106:109]
	v_mfma_f32_16x16x32_bf16 v[94:97], v[158:161], v[218:221], v[94:97]
	v_mfma_f32_16x16x32_bf16 v[90:93], v[166:169], v[218:221], v[90:93]
	v_mfma_f32_16x16x32_bf16 v[78:81], v[158:161], v[226:229], v[78:81]
	v_mfma_f32_16x16x32_bf16 v[74:77], v[166:169], v[226:229], v[74:77]
	v_mfma_f32_16x16x32_bf16 v[118:121], v[170:173], v[198:201], v[118:121]
	v_mfma_f32_16x16x32_bf16 v[114:117], v[190:193], v[198:201], v[114:117]
	v_mfma_f32_16x16x32_bf16 v[102:105], v[170:173], v[206:209], v[102:105]
	v_mfma_f32_16x16x32_bf16 v[98:101], v[190:193], v[206:209], v[98:101]
	v_mfma_f32_16x16x32_bf16 v[86:89], v[170:173], v[214:217], v[86:89]
	v_mfma_f32_16x16x32_bf16 v[82:85], v[190:193], v[214:217], v[82:85]
	v_mfma_f32_16x16x32_bf16 v[70:73], v[170:173], v[222:225], v[70:73]
	v_mfma_f32_16x16x32_bf16 v[66:69], v[190:193], v[222:225], v[66:69]
	v_mfma_f32_16x16x32_bf16 v[118:121], v[186:189], v[202:205], v[118:121]
	v_mfma_f32_16x16x32_bf16 v[114:117], v[194:197], v[202:205], v[114:117]
	v_mfma_f32_16x16x32_bf16 v[102:105], v[186:189], v[210:213], v[102:105]
	v_mfma_f32_16x16x32_bf16 v[98:101], v[194:197], v[210:213], v[98:101]
	v_mfma_f32_16x16x32_bf16 v[86:89], v[186:189], v[218:221], v[86:89]
	v_mfma_f32_16x16x32_bf16 v[82:85], v[194:197], v[218:221], v[82:85]
	v_mfma_f32_16x16x32_bf16 v[70:73], v[186:189], v[226:229], v[70:73]
	v_mfma_f32_16x16x32_bf16 v[66:69], v[194:197], v[226:229], v[66:69]
	s_barrier
	s_add_i32 s39, s71, s3
	s_mov_b32 m0, s39
	ds_read_b128 v[198:201], v184 offset:16384
	ds_read_b128 v[202:205], v184 offset:17408
	ds_read_b128 v[206:209], v184 offset:18432
	ds_read_b128 v[210:213], v184 offset:19456
	ds_read_b128 v[214:217], v184 offset:20480
	ds_read_b128 v[218:221], v184 offset:21504
	ds_read_b128 v[222:225], v184 offset:22528
	ds_read_b128 v[226:229], v184 offset:23552
	global_load_lds_dwordx4 v132, s[56:57]
	s_add_i32 m0, s39, 0x2000
	s_add_u32 s40, s56, 0x80000
	s_addc_u32 s41, s57, 0
	s_add_i32 s39, s72, s3
	global_load_lds_dwordx4 v136, s[56:57]
	s_mov_b32 m0, s39
	s_nop 0
	global_load_lds_dwordx4 v132, s[40:41]
	s_add_i32 m0, s39, 0x2000
	s_nop 0
	global_load_lds_dwordx4 v136, s[40:41]
	s_mov_b32 m0, s21
	s_nop 0
	global_load_lds_dwordx4 v138, s[58:59]
	s_mov_b32 m0, s35
	s_nop 0
	global_load_lds_dwordx4 v140, s[58:59]
	s_waitcnt vmcnt(8)
	s_waitcnt lgkmcnt(0)
	s_barrier
	s_waitcnt lgkmcnt(0)
	v_mfma_f32_16x16x32_bf16 v[62:65], v[154:157], v[198:201], v[62:65]
	v_mfma_f32_16x16x32_bf16 v[58:61], v[162:165], v[198:201], v[58:61]
	v_mfma_f32_16x16x32_bf16 v[46:49], v[154:157], v[206:209], v[46:49]
	v_mfma_f32_16x16x32_bf16 v[42:45], v[162:165], v[206:209], v[42:45]
	v_mfma_f32_16x16x32_bf16 v[30:33], v[154:157], v[214:217], v[30:33]
	v_mfma_f32_16x16x32_bf16 v[26:29], v[162:165], v[214:217], v[26:29]
	v_mfma_f32_16x16x32_bf16 v[14:17], v[154:157], v[222:225], v[14:17]
	v_mfma_f32_16x16x32_bf16 v[10:13], v[162:165], v[222:225], v[10:13]
	v_mfma_f32_16x16x32_bf16 v[62:65], v[158:161], v[202:205], v[62:65]
	v_mfma_f32_16x16x32_bf16 v[58:61], v[166:169], v[202:205], v[58:61]
	v_mfma_f32_16x16x32_bf16 v[46:49], v[158:161], v[210:213], v[46:49]
	v_mfma_f32_16x16x32_bf16 v[42:45], v[166:169], v[210:213], v[42:45]
	v_mfma_f32_16x16x32_bf16 v[30:33], v[158:161], v[218:221], v[30:33]
	v_mfma_f32_16x16x32_bf16 v[26:29], v[166:169], v[218:221], v[26:29]
	v_mfma_f32_16x16x32_bf16 v[14:17], v[158:161], v[226:229], v[14:17]
	v_mfma_f32_16x16x32_bf16 v[10:13], v[166:169], v[226:229], v[10:13]
	v_mfma_f32_16x16x32_bf16 v[54:57], v[170:173], v[198:201], v[54:57]
	v_mfma_f32_16x16x32_bf16 v[50:53], v[190:193], v[198:201], v[50:53]
	v_mfma_f32_16x16x32_bf16 v[38:41], v[170:173], v[206:209], v[38:41]
	v_mfma_f32_16x16x32_bf16 v[34:37], v[190:193], v[206:209], v[34:37]
	v_mfma_f32_16x16x32_bf16 v[22:25], v[170:173], v[214:217], v[22:25]
	v_mfma_f32_16x16x32_bf16 v[18:21], v[190:193], v[214:217], v[18:21]
	v_mfma_f32_16x16x32_bf16 v[6:9], v[170:173], v[222:225], v[6:9]
	v_mfma_f32_16x16x32_bf16 v[2:5], v[190:193], v[222:225], v[2:5]
	v_mfma_f32_16x16x32_bf16 v[54:57], v[186:189], v[202:205], v[54:57]
	v_mfma_f32_16x16x32_bf16 v[50:53], v[194:197], v[202:205], v[50:53]
	v_mfma_f32_16x16x32_bf16 v[38:41], v[186:189], v[210:213], v[38:41]
	v_mfma_f32_16x16x32_bf16 v[34:37], v[194:197], v[210:213], v[34:37]
	v_mfma_f32_16x16x32_bf16 v[22:25], v[186:189], v[218:221], v[22:25]
	v_mfma_f32_16x16x32_bf16 v[18:21], v[194:197], v[218:221], v[18:21]
	v_mfma_f32_16x16x32_bf16 v[6:9], v[186:189], v[226:229], v[6:9]
	v_mfma_f32_16x16x32_bf16 v[2:5], v[194:197], v[226:229], v[2:5]
	s_barrier
; #define PG8_STAGE(bufoff, gbase, RR, ld) do { _Pragma("unroll") for (int _i = 0; _i < 2; ++_i) \
;         __builtin_amdgcn_global_load_lds((const unsigned*)((const char*)(gbase) + (RR)[_i] * (ld) + C2[_i]), (LAS unsigned*)(lds + (bufoff) + ldsw + _i * 8192), 16, 0, 0); } while (0)
; #define PG8_LDA(dst, b, h) do { _Pragma("unroll") for (int m = 0; m < 4; ++m) _Pragma("unroll") for (int k = 0; k < 2; ++k) dst[m][k] = *(const LAS bf16x8*)(lds + PG8_SA(b, h) + aoff + m * 2048 + k * 1024); } while (0)
; #define PG8_LDB(dst, b, h) do { _Pragma("unroll") for (int n = 0; n < 2; ++n) _Pragma("unroll") for (int k = 0; k < 2; ++k) dst[n][k] = *(const LAS bf16x8*)(lds + PG8_SB(b, h) + boff + n * 2048 + k * 1024); } while (0)
; #define PG8_MMA(ai, bj, At, Bt) do { __builtin_amdgcn_s_setprio(1); _Pragma("unroll") for (int m = 0; m < 4; ++m) _Pragma("unroll") for (int n = 0; n < 2; ++n) _Pragma("unroll") for (int k = 0; k < 2; ++k) \
;         acc[ai][bj][m][n] = __builtin_amdgcn_mfma_f32_16x16x32_bf16(Bt[n][k], At[m][k], acc[ai][bj][m][n], 0, 0, 0); __builtin_amdgcn_s_setprio(0); } while (0)
; #define PG8_WAIT_V(n) asm volatile("s_waitcnt vmcnt(" #n ")" ::: "memory")
; #define PG8_WAIT_L(n) asm volatile("s_waitcnt lgkmcnt(" #n ")" ::: "memory")
; #define PG8_BAR __builtin_amdgcn_s_barrier()
; #define PG8_SCHED __builtin_amdgcn_sched_barrier(0)
; template <class Sched, class Epi>
; __device__ __forceinline__ void gemm_run(LAS unsigned char* lds, const Sched& S, const Epi& E) {
;     ...
;             PG8_LDB(B0, 1, 0); PG8_LDB(B1, 1, 1); PG8_SCHED; PG8_LDA(At, 1, 0); PG8_STAGE(PG8_SA(0, 1), a2 + (size_t)HALF * la2, RA, la2);
;             PG8_WAIT_V(8); PG8_WAIT_L(0); PG8_BAR; PG8_MMA(0, 0, At, B0); PG8_MMA(0, 1, At, B1); PG8_BAR; PG8_SCHED;
;             PG8_LDA(At, 1, 1); PG8_STAGE(PG8_SB(1, 0), b3, RB, lb2); PG8_STAGE(PG8_SB(1, 1), b3 + (size_t)HALF * lb2, RB, lb2); PG8_STAGE(PG8_SA(1, 0), a3, RA, la2);
;             PG8_WAIT_V(8); PG8_WAIT_L(0); PG8_BAR; PG8_MMA(1, 0, At, B0); PG8_MMA(1, 1, At, B1); PG8_BAR; PG8_SCHED;
;         }
;         if (wr == 0) PG8_BAR;
	s_add_i32 s39, 0, 0x18000
	v_add_u32_e32 v134, s39, v179
	s_add_i32 s42, 0, 0x1c000
	ds_read_b128 v[154:157], v134
	ds_read_b128 v[158:161], v134 offset:1024
	ds_read_b128 v[162:165], v134 offset:2048
	ds_read_b128 v[166:169], v134 offset:3072
	v_add_u32_e32 v134, s42, v179
	ds_read_b128 v[170:173], v134
	ds_read_b128 v[186:189], v134 offset:1024
	ds_read_b128 v[190:193], v134 offset:2048
	ds_read_b128 v[194:197], v134 offset:3072
	s_add_u32 s40, s58, 0x80000
	s_addc_u32 s41, s59, 0
	s_mov_b32 m0, s60
	ds_read_b128 v[198:201], v184 offset:32768
	ds_read_b128 v[202:205], v184 offset:33792
	ds_read_b128 v[206:209], v184 offset:34816
	ds_read_b128 v[210:213], v184 offset:35840
	ds_read_b128 v[214:217], v184 offset:36864
	ds_read_b128 v[218:221], v184 offset:37888
	ds_read_b128 v[222:225], v184 offset:38912
	ds_read_b128 v[226:229], v184 offset:39936
	global_load_lds_dwordx4 v138, s[40:41]
	s_mov_b32 m0, s61
	s_nop 0
	global_load_lds_dwordx4 v140, s[40:41]
	s_waitcnt vmcnt(8)
	s_waitcnt lgkmcnt(0)
	s_barrier
	s_waitcnt lgkmcnt(0)
	v_mfma_f32_16x16x32_bf16 v[126:129], v[154:157], v[198:201], v[126:129]
	v_mfma_f32_16x16x32_bf16 v[122:125], v[162:165], v[198:201], v[122:125]
	v_mfma_f32_16x16x32_bf16 v[110:113], v[154:157], v[206:209], v[110:113]
	v_mfma_f32_16x16x32_bf16 v[106:109], v[162:165], v[206:209], v[106:109]
	v_mfma_f32_16x16x32_bf16 v[94:97], v[154:157], v[214:217], v[94:97]
	v_mfma_f32_16x16x32_bf16 v[90:93], v[162:165], v[214:217], v[90:93]
	v_mfma_f32_16x16x32_bf16 v[78:81], v[154:157], v[222:225], v[78:81]
	v_mfma_f32_16x16x32_bf16 v[74:77], v[162:165], v[222:225], v[74:77]
	v_mfma_f32_16x16x32_bf16 v[126:129], v[158:161], v[202:205], v[126:129]
	v_mfma_f32_16x16x32_bf16 v[122:125], v[166:169], v[202:205], v[122:125]
	v_mfma_f32_16x16x32_bf16 v[110:113], v[158:161], v[210:213], v[110:113]
	v_mfma_f32_16x16x32_bf16 v[106:109], v[166:169], v[210:213], v[106:109]
	v_mfma_f32_16x16x32_bf16 v[94:97], v[158:161], v[218:221], v[94:97]
	v_mfma_f32_16x16x32_bf16 v[90:93], v[166:169], v[218:221], v[90:93]
	v_mfma_f32_16x16x32_bf16 v[78:81], v[158:161], v[226:229], v[78:81]
	v_mfma_f32_16x16x32_bf16 v[74:77], v[166:169], v[226:229], v[74:77]
	v_mfma_f32_16x16x32_bf16 v[118:121], v[170:173], v[198:201], v[118:121]
	v_mfma_f32_16x16x32_bf16 v[114:117], v[190:193], v[198:201], v[114:117]
	v_mfma_f32_16x16x32_bf16 v[102:105], v[170:173], v[206:209], v[102:105]
	v_mfma_f32_16x16x32_bf16 v[98:101], v[190:193], v[206:209], v[98:101]
	v_mfma_f32_16x16x32_bf16 v[86:89], v[170:173], v[214:217], v[86:89]
	v_mfma_f32_16x16x32_bf16 v[82:85], v[190:193], v[214:217], v[82:85]
	v_mfma_f32_16x16x32_bf16 v[70:73], v[170:173], v[222:225], v[70:73]
	v_mfma_f32_16x16x32_bf16 v[66:69], v[190:193], v[222:225], v[66:69]
	v_mfma_f32_16x16x32_bf16 v[118:121], v[186:189], v[202:205], v[118:121]
	v_mfma_f32_16x16x32_bf16 v[114:117], v[194:197], v[202:205], v[114:117]
	v_mfma_f32_16x16x32_bf16 v[102:105], v[186:189], v[210:213], v[102:105]
	v_mfma_f32_16x16x32_bf16 v[98:101], v[194:197], v[210:213], v[98:101]
	v_mfma_f32_16x16x32_bf16 v[86:89], v[186:189], v[218:221], v[86:89]
	v_mfma_f32_16x16x32_bf16 v[82:85], v[194:197], v[218:221], v[82:85]
	v_mfma_f32_16x16x32_bf16 v[70:73], v[186:189], v[226:229], v[70:73]
	v_mfma_f32_16x16x32_bf16 v[66:69], v[194:197], v[226:229], v[66:69]
	s_barrier
	s_add_i32 s39, s39, s3
	s_mov_b32 m0, s39
	ds_read_b128 v[198:201], v184 offset:49152
	ds_read_b128 v[202:205], v184 offset:50176
	ds_read_b128 v[206:209], v184 offset:51200
	ds_read_b128 v[210:213], v184 offset:52224
	ds_read_b128 v[214:217], v184 offset:53248
	ds_read_b128 v[218:221], v184 offset:54272
	ds_read_b128 v[222:225], v184 offset:55296
	ds_read_b128 v[226:229], v184 offset:56320
	s_add_u32 s98, s56, 0x80
	s_addc_u32 s99, s57, 0
	global_load_lds_dwordx4 v132, s[98:99]
	s_add_i32 m0, s39, 0x2000
	s_add_u32 s40, s56, 0x80080
	s_addc_u32 s41, s57, 0
	global_load_lds_dwordx4 v136, s[98:99]
	s_add_i32 s39, s42, s3
	s_mov_b32 m0, s39
	s_nop 0
	global_load_lds_dwordx4 v132, s[40:41]
	s_add_i32 m0, s39, 0x2000
	s_nop 0
	global_load_lds_dwordx4 v136, s[40:41]
	s_mov_b32 m0, s64
	s_nop 0
	s_add_u32 s100, s58, 0x80
	s_addc_u32 s101, s59, 0
	global_load_lds_dwordx4 v138, s[100:101]
	s_mov_b32 m0, s65
	s_nop 0
	global_load_lds_dwordx4 v140, s[100:101]
	s_waitcnt vmcnt(8)
	s_waitcnt lgkmcnt(0)
	s_barrier
	s_waitcnt lgkmcnt(0)
	v_mfma_f32_16x16x32_bf16 v[62:65], v[154:157], v[198:201], v[62:65]
	v_mfma_f32_16x16x32_bf16 v[58:61], v[162:165], v[198:201], v[58:61]
	v_mfma_f32_16x16x32_bf16 v[46:49], v[154:157], v[206:209], v[46:49]
	v_mfma_f32_16x16x32_bf16 v[42:45], v[162:165], v[206:209], v[42:45]
	v_mfma_f32_16x16x32_bf16 v[30:33], v[154:157], v[214:217], v[30:33]
	v_mfma_f32_16x16x32_bf16 v[26:29], v[162:165], v[214:217], v[26:29]
	v_mfma_f32_16x16x32_bf16 v[14:17], v[154:157], v[222:225], v[14:17]
	v_mfma_f32_16x16x32_bf16 v[10:13], v[162:165], v[222:225], v[10:13]
	v_mfma_f32_16x16x32_bf16 v[62:65], v[158:161], v[202:205], v[62:65]
	v_mfma_f32_16x16x32_bf16 v[58:61], v[166:169], v[202:205], v[58:61]
	v_mfma_f32_16x16x32_bf16 v[46:49], v[158:161], v[210:213], v[46:49]
	v_mfma_f32_16x16x32_bf16 v[42:45], v[166:169], v[210:213], v[42:45]
	v_mfma_f32_16x16x32_bf16 v[30:33], v[158:161], v[218:221], v[30:33]
	v_mfma_f32_16x16x32_bf16 v[26:29], v[166:169], v[218:221], v[26:29]
	v_mfma_f32_16x16x32_bf16 v[14:17], v[158:161], v[226:229], v[14:17]
	v_mfma_f32_16x16x32_bf16 v[10:13], v[166:169], v[226:229], v[10:13]
	v_mfma_f32_16x16x32_bf16 v[54:57], v[170:173], v[198:201], v[54:57]
	v_mfma_f32_16x16x32_bf16 v[50:53], v[190:193], v[198:201], v[50:53]
	v_mfma_f32_16x16x32_bf16 v[38:41], v[170:173], v[206:209], v[38:41]
	v_mfma_f32_16x16x32_bf16 v[34:37], v[190:193], v[206:209], v[34:37]
	v_mfma_f32_16x16x32_bf16 v[22:25], v[170:173], v[214:217], v[22:25]
	v_mfma_f32_16x16x32_bf16 v[18:21], v[190:193], v[214:217], v[18:21]
	v_mfma_f32_16x16x32_bf16 v[6:9], v[170:173], v[222:225], v[6:9]
	v_mfma_f32_16x16x32_bf16 v[2:5], v[190:193], v[222:225], v[2:5]
	v_mfma_f32_16x16x32_bf16 v[54:57], v[186:189], v[202:205], v[54:57]
	v_mfma_f32_16x16x32_bf16 v[50:53], v[194:197], v[202:205], v[50:53]
	v_mfma_f32_16x16x32_bf16 v[38:41], v[186:189], v[210:213], v[38:41]
	v_mfma_f32_16x16x32_bf16 v[34:37], v[194:197], v[210:213], v[34:37]
	v_mfma_f32_16x16x32_bf16 v[22:25], v[186:189], v[218:221], v[22:25]
	v_mfma_f32_16x16x32_bf16 v[18:21], v[194:197], v[218:221], v[18:21]
	v_mfma_f32_16x16x32_bf16 v[6:9], v[186:189], v[226:229], v[6:9]
	v_mfma_f32_16x16x32_bf16 v[2:5], v[194:197], v[226:229], v[2:5]
	s_barrier
	s_add_i32 s38, s38, 2
	s_add_u32 s54, s54, 0x100
	s_addc_u32 s55, s55, 0
	s_cmp_gt_u32 s38, 29
	s_cbranch_scc0 .LBB0_246
	s_and_b64 vcc, exec, s[16:17]
	s_cbranch_vccz .LBB0_249
	s_barrier
